# v112 + phase-A light compute for the last n-tile (only the 16 valid output columns are multiplied; edit_gemmA9)
# baseline (speedup 1.0000x reference)
; template <bool ABF, bool BBF, class RowF, class ColF, class Epi>
; __device__ __forceinline__ void gemm_tile(char* smem, int K, RowF rowptr, ColF colptr, int ldb, Epi epi) {
;     ...
;   const int ar0 = ABF ? (tid >> 3) : (tid >> 4);
;   const int ac = ABF ? (tid & 7) * 8 : (tid & 15) * 4;
;   constexpr int ARS = ABF ? 32 : 16;
;   const char* ap[NA];
; #pragma unroll
;   for (int i = 0; i < NA; i++) ap[i] = (const char*)rowptr(ar0 + ARS * i) + ac * (ABF ? 2 : 4);
;   const int bc = tid & 127, kh = tid >> 7;
;   const float* bp = BBF ? nullptr : ((const float*)colptr(bc) + (size_t)(kh * 32) * ldb);
;   const int br0 = tid >> 3, bcc = (tid & 7) * 8;
;   const char* bq[4];
;   if (BBF) {
; #pragma unroll
;     for (int i = 0; i < 4; i++) bq[i] = (const char*)colptr(br0 + 32 * i) + bcc * 2;
;   }
; __device__ void phaseA(const Params& p, char* smem) {
;     ...
;     if (q < 384) { mt = q / 3; nt = 7 * pj + odd * 4 + q % 3; }
;     else if (q < 448) { mt = odd * 64 + (q - 384); nt = 7 * pj + 3; }
;     else { mt = 16 * j + (q - 448); nt = 28; }
;     const int m0 = mt * 128, n0 = nt * 128;
;     const u16* xa = p.XB + (size_t)m0 * DM;
;     auto rowf = [&](int r) { return (const void*)(xa + (size_t)r * DM); };
;     auto colf = [&](int c) { int n = n0 + c; if (n > INC - 1) n = INC - 1; return (const void*)(p.WinT + (size_t)n * DM); };
.LBB0_108:
	s_andn2_saveexec_b64 s[0:1], s[0:1]
	s_mov_b32 s2, 0x55555556
	v_mul_hi_i32 v1, v0, s2
	v_lshrrev_b32_e32 v2, 31, v1
	v_add_u32_e32 v1, v1, v2
	v_lshl_add_u32 v2, v1, 1, v1
	v_sub_u32_e32 v0, v0, v2
	v_add_u32_e32 v121, s97, v0
	s_or_b64 exec, exec, s[0:1]
	v_lshrrev_b32_e32 v86, 4, v128
	v_xor_b32_e32 v86, v86, v128
	v_and_b32_e32 v86, 7, v86
	v_lshlrev_b32_e32 v80, 4, v86
	v_mov_b32_e32 v81, 0
	v_sub_u32_e32 v82, v80, v124
	v_lshrrev_b32_e32 v86, 6, v128
	v_ashrrev_i32_e32 v83, 31, v82
	v_readfirstlane_b32 s100, v86
	s_lshl_b32 s100, s100, 10
	v_add_u32_e32 v86, 0x80, v80
	v_mov_b32_e32 v87, 0
	v_mov_b32_e32 v88, 0x10000
	v_mov_b32_e32 v89, 0
	v_readfirstlane_b32 s98, v121
	s_bfe_u32 s99, s100, 0x1000a
	s_cmp_eq_u32 s98, 28
	s_cselect_b32 s98, 1, 0
	s_add_i32 s99, s99, 1
	s_mul_i32 s99, s99, s98
	v_lshlrev_b32_e32 v104, 7, v1
	v_ashrrev_i32_e32 v105, 31, v104
	v_lshlrev_b64 v[0:1], 11, v[104:105]
	v_lshl_add_u64 v[2:3], v[98:99], 0, v[0:1]
	v_lshlrev_b32_e32 v137, 7, v121
	v_add_co_u32_e32 v16, vcc, s40, v2
	v_or_b32_e32 v4, v137, v160
	s_nop 0
	v_addc_co_u32_e32 v17, vcc, 0, v3, vcc
	v_min_i32_e32 v10, 0xdef, v4
	v_add_co_u32_e32 v18, vcc, s41, v2
	v_min_i32_e32 v6, 0xe0f, v4
	v_ashrrev_i32_e32 v11, 31, v10
	v_addc_co_u32_e32 v19, vcc, 0, v3, vcc
	v_ashrrev_i32_e32 v7, 31, v6
	v_lshlrev_b64 v[10:11], 11, v[10:11]
	v_min_i32_e32 v12, 0xdcf, v4
	s_add_u32 m0, s100, 0x0
	v_lshl_add_u64 v[84:85], v[2:3], 0, v[82:83]
	global_load_lds_dwordx4 v[84:85], off
	v_add_co_u32_e32 v2, vcc, s42, v2
	v_lshlrev_b64 v[6:7], 11, v[6:7]
	v_lshl_add_u64 v[10:11], v[100:101], 0, v[10:11]
	v_ashrrev_i32_e32 v13, 31, v12
	v_addc_co_u32_e32 v3, vcc, 0, v3, vcc
	v_lshl_add_u64 v[8:9], v[100:101], 0, v[6:7]
	v_lshlrev_b64 v[12:13], 11, v[12:13]
	v_min_i32_e32 v14, 0xdaf, v4
	s_add_u32 m0, s100, 0x1000
	v_lshl_add_u64 v[84:85], v[16:17], 0, v[82:83]
	global_load_lds_dwordx4 v[84:85], off
	s_add_u32 m0, s100, 0x2000
	v_lshl_add_u64 v[84:85], v[18:19], 0, v[82:83]
	global_load_lds_dwordx4 v[84:85], off
	s_add_u32 m0, s100, 0x3000
	v_lshl_add_u64 v[84:85], v[2:3], 0, v[82:83]
	global_load_lds_dwordx4 v[84:85], off
	s_add_u32 m0, s100, 0x4000
	v_lshl_add_u64 v[84:85], v[8:9], 0, v[82:83]
	global_load_lds_dwordx4 v[84:85], off
	v_add_co_u32_e32 v2, vcc, s40, v10
	v_lshl_add_u64 v[12:13], v[100:101], 0, v[12:13]
	v_ashrrev_i32_e32 v15, 31, v14
	v_addc_co_u32_e32 v3, vcc, 0, v11, vcc
	v_lshlrev_b64 v[14:15], 11, v[14:15]
	v_add_co_u32_e32 v8, vcc, s41, v12
	v_lshl_add_u64 v[14:15], v[100:101], 0, v[14:15]
	s_nop 0
	v_addc_co_u32_e32 v9, vcc, 0, v13, vcc
	s_add_u32 m0, s100, 0x5000
	v_lshl_add_u64 v[84:85], v[2:3], 0, v[82:83]
	global_load_lds_dwordx4 v[84:85], off
	s_add_u32 m0, s100, 0x6000
	v_lshl_add_u64 v[84:85], v[8:9], 0, v[82:83]
	global_load_lds_dwordx4 v[84:85], off
	v_add_co_u32_e32 v2, vcc, s42, v14
	s_mov_b64 s[0:1], 0xdef
	s_nop 0
	v_addc_co_u32_e32 v3, vcc, 0, v15, vcc
	s_add_u32 m0, s100, 0x7000
	v_lshl_add_u64 v[84:85], v[2:3], 0, v[82:83]
	global_load_lds_dwordx4 v[84:85], off
	s_mov_b64 s[2:3], 0xdcf
	s_mov_b64 s[6:7], 0xdaf
	v_ashrrev_i32_e32 v5, 31, v4
	v_cmp_gt_i64_e32 vcc, s[0:1], v[4:5]
	v_cmp_gt_i64_e64 s[0:1], s[2:3], v[4:5]
	v_cmp_gt_i64_e64 s[6:7], s[6:7], v[4:5]
	v_lshl_add_u64 v[106:107], v[102:103], 0, v[0:1]
	v_cndmask_b32_e32 v1, 0, v5, vcc
	v_cndmask_b32_e64 v3, 0, v5, s[0:1]
	v_cndmask_b32_e64 v5, 0, v5, s[6:7]
	v_cndmask_b32_e32 v0, v117, v4, vcc
	v_cndmask_b32_e64 v2, v118, v4, s[0:1]
	v_cndmask_b32_e64 v4, v119, v4, s[6:7]
	v_mov_b32_e32 v60, 0
	v_lshlrev_b64 v[0:1], 11, v[0:1]
	v_lshlrev_b64 v[2:3], 11, v[2:3]
	v_lshlrev_b64 v[4:5], 11, v[4:5]
	s_mov_b32 s4, 0
	s_mov_b32 s5, 0
	v_mov_b32_e32 v61, v60
	v_mov_b32_e32 v62, v60
	v_mov_b32_e32 v63, v60
	v_lshl_add_u64 v[108:109], s[24:25], 0, v[6:7]
	v_lshl_add_u64 v[110:111], s[26:27], 0, v[0:1]
	v_lshl_add_u64 v[112:113], s[28:29], 0, v[2:3]
	v_lshl_add_u64 v[114:115], s[30:31], 0, v[4:5]
	v_mov_b32_e32 v56, v60
	v_mov_b32_e32 v57, v60
	v_mov_b32_e32 v58, v60
	v_mov_b32_e32 v59, v60
	v_mov_b32_e32 v52, v60
	v_mov_b32_e32 v53, v60
	v_mov_b32_e32 v54, v60
	v_mov_b32_e32 v55, v60
	v_mov_b32_e32 v48, v60
	v_mov_b32_e32 v49, v60
	v_mov_b32_e32 v50, v60
	v_mov_b32_e32 v51, v60
	v_mov_b32_e32 v44, v60
	v_mov_b32_e32 v45, v60
	v_mov_b32_e32 v46, v60
	v_mov_b32_e32 v47, v60
	v_mov_b32_e32 v40, v60
	v_mov_b32_e32 v41, v60
	v_mov_b32_e32 v42, v60
	v_mov_b32_e32 v43, v60
	v_mov_b32_e32 v36, v60
	v_mov_b32_e32 v37, v60
	v_mov_b32_e32 v38, v60
	v_mov_b32_e32 v39, v60
	v_mov_b32_e32 v32, v60
	v_mov_b32_e32 v33, v60
	v_mov_b32_e32 v34, v60
	v_mov_b32_e32 v35, v60
	v_mov_b32_e32 v28, v60
	v_mov_b32_e32 v29, v60
	v_mov_b32_e32 v30, v60
	v_mov_b32_e32 v31, v60
	v_mov_b32_e32 v24, v60
	v_mov_b32_e32 v25, v60
	v_mov_b32_e32 v26, v60
	v_mov_b32_e32 v27, v60
	v_mov_b32_e32 v20, v60
	v_mov_b32_e32 v21, v60
	v_mov_b32_e32 v22, v60
	v_mov_b32_e32 v23, v60
	v_mov_b32_e32 v16, v60
	v_mov_b32_e32 v17, v60
	v_mov_b32_e32 v18, v60
	v_mov_b32_e32 v19, v60
	v_mov_b32_e32 v12, v60
	v_mov_b32_e32 v13, v60
	v_mov_b32_e32 v14, v60
	v_mov_b32_e32 v15, v60
	v_mov_b32_e32 v8, v60
	v_mov_b32_e32 v9, v60
	v_mov_b32_e32 v10, v60
	v_mov_b32_e32 v11, v60
	v_mov_b32_e32 v4, v60
	v_mov_b32_e32 v5, v60
	v_mov_b32_e32 v6, v60
	v_mov_b32_e32 v7, v60
	v_mov_b32_e32 v0, v60
	v_mov_b32_e32 v1, v60
	v_mov_b32_e32 v2, v60
	v_mov_b32_e32 v3, v60
	s_waitcnt vmcnt(0) lgkmcnt(0)
	s_barrier
	s_branch .LBB0_112
; template <bool ABF, bool BBF, class RowF, class ColF, class Epi>
; __device__ __forceinline__ void gemm_tile(char* smem, int K, RowF rowptr, ColF colptr, int ldb, Epi epi) {
;     ...
;   for (int k0 = 0; k0 < K; k0 += BK) {
;     if (k0 + BK < K) gload(k0 + BK);
;     const u16* As = As0 + cur * (GEMM_SMEM / 2);
;     const u16* Bs = As + BM * LDT;
;     {
;       bf16x8 af[2][4], bfr[2][4];
; #pragma unroll
;       for (int ks = 0; ks < 2; ks++) {
; #pragma unroll
;         for (int mi = 0; mi < 4; mi++) af[ks][mi] = *(const bf16x8*)&As[(wm * 64 + mi * 16 + l15) * LDT + (((ks * 4 + kg) ^ swz) << 3)];
; #pragma unroll
;         for (int ni = 0; ni < 4; ni++) bfr[ks][ni] = *(const bf16x8*)&Bs[(wn * 64 + ni * 16 + l15) * LDT + (((ks * 4 + kg) ^ swz) << 3)];
;       }
;       __builtin_amdgcn_sched_barrier(0);
; #pragma unroll
;       for (int ks = 0; ks < 2; ks++)
; #pragma unroll
;         for (int mi = 0; mi < 4; mi++)
; #pragma unroll
;           for (int ni = 0; ni < 4; ni++)
;             acc[mi][ni] = __builtin_amdgcn_mfma_f32_16x16x32_bf16(bfr[ks][ni], af[ks][mi], acc[mi][ni], 0, 0, 0);
;       __builtin_amdgcn_sched_barrier(0);
;     }
;     if (k0 + BK < K) sstore(cur ^ 1);
;     __syncthreads();
;     cur ^= 1;
;   }
.La9_var1:
	s_cmp_eq_u32 s99, 2
	s_cbranch_scc1 .La9_ret1
	s_lshl_b32 s6, s5, 15
	s_add_i32 s6, s6, 0
	v_lshlrev_b32_e32 v96, 1, v163
	v_lshlrev_b32_e32 v105, 1, v164
	v_add3_u32 v139, s6, v96, v105
	v_add3_u32 v141, s6, v105, v96
	ds_read_b128 v[142:145], v139
	ds_read_b128 v[146:149], v141 offset:2048
	ds_read_b128 v[150:153], v141 offset:4096
	ds_read_b128 v[154:157], v141 offset:6144
	v_lshlrev_b32_e32 v139, 1, v162
	v_add_u32_e32 v141, s6, v139
	v_add_u32_e32 v96, v141, v96
	ds_read_b128 v[172:175], v96 offset:16384
	v_lshlrev_b32_e32 v96, 1, v165
	v_add_u32_e32 v158, s6, v96
	v_add_u32_e32 v105, v158, v105
	ds_read_b128 v[188:191], v105
	ds_read_b128 v[192:195], v105 offset:2048
	ds_read_b128 v[196:199], v105 offset:4096
	ds_read_b128 v[200:203], v105 offset:6144
	v_add_u32_e32 v105, v158, v139
	v_add_u32_e32 v96, v141, v96
	ds_read_b128 v[204:207], v105 offset:16384
	s_waitcnt lgkmcnt(0)
	v_mfma_f32_16x16x32_bf16 v[60:63], v[172:175], v[142:145], v[60:63]
	v_mfma_f32_16x16x32_bf16 v[44:47], v[172:175], v[146:149], v[44:47]
	v_mfma_f32_16x16x32_bf16 v[28:31], v[172:175], v[150:153], v[28:31]
	v_mfma_f32_16x16x32_bf16 v[12:15], v[172:175], v[154:157], v[12:15]
	v_mfma_f32_16x16x32_bf16 v[60:63], v[204:207], v[188:191], v[60:63]
	v_mfma_f32_16x16x32_bf16 v[44:47], v[204:207], v[192:195], v[44:47]
	v_mfma_f32_16x16x32_bf16 v[28:31], v[204:207], v[196:199], v[28:31]
	v_mfma_f32_16x16x32_bf16 v[12:15], v[204:207], v[200:203], v[12:15]
	s_branch .La9_ret1
.La9_var2:
	s_cmp_eq_u32 s99, 2
	s_cbranch_scc1 .La9_ret2
	s_lshl_b32 s6, s5, 15
	s_add_i32 s6, s6, 0
	v_lshlrev_b32_e32 v96, 1, v163
	v_lshlrev_b32_e32 v105, 1, v164
	v_add3_u32 v139, s6, v96, v105
	v_add3_u32 v141, s6, v105, v96
	ds_read_b128 v[142:145], v139
	ds_read_b128 v[146:149], v141 offset:2048
	ds_read_b128 v[150:153], v141 offset:4096
	ds_read_b128 v[154:157], v141 offset:6144
	v_lshlrev_b32_e32 v139, 1, v162
	v_add_u32_e32 v141, s6, v139
	v_add_u32_e32 v96, v141, v96
	ds_read_b128 v[172:175], v96 offset:16384
	v_lshlrev_b32_e32 v96, 1, v165
	v_add_u32_e32 v158, s6, v96
	v_add_u32_e32 v105, v158, v105
	ds_read_b128 v[188:191], v105
	ds_read_b128 v[192:195], v105 offset:2048
	ds_read_b128 v[196:199], v105 offset:4096
	ds_read_b128 v[200:203], v105 offset:6144
	v_add_u32_e32 v105, v158, v139
	v_add_u32_e32 v96, v141, v96
	ds_read_b128 v[204:207], v105 offset:16384
	s_waitcnt lgkmcnt(0)
	v_mfma_f32_16x16x32_bf16 v[60:63], v[172:175], v[142:145], v[60:63]
	v_mfma_f32_16x16x32_bf16 v[44:47], v[172:175], v[146:149], v[44:47]
	v_mfma_f32_16x16x32_bf16 v[28:31], v[172:175], v[150:153], v[28:31]
	v_mfma_f32_16x16x32_bf16 v[12:15], v[172:175], v[154:157], v[12:15]
	v_mfma_f32_16x16x32_bf16 v[60:63], v[204:207], v[188:191], v[60:63]
	v_mfma_f32_16x16x32_bf16 v[44:47], v[204:207], v[192:195], v[44:47]
	v_mfma_f32_16x16x32_bf16 v[28:31], v[204:207], v[196:199], v[28:31]
	v_mfma_f32_16x16x32_bf16 v[12:15], v[204:207], v[200:203], v[12:15]
	s_branch .La9_ret2
	.p2align 6
.LBB0_112:
.La6_top_X:
	s_xor_b32 s101, s5, 1
	s_lshl_b32 s101, s101, 15
	s_add_u32 s101, s101, s100
	s_cmpk_lt_u32 s4, 0x3c0
	s_cbranch_scc0 .La6_c_X
	s_add_u32 m0, s101, 0x0
	v_lshl_add_u64 v[242:243], v[106:107], 0, v[86:87]
	global_load_lds_dwordx4 v[242:243], off
	s_add_u32 m0, s101, 0x1000
	v_lshl_add_u64 v[242:243], v[242:243], 0, v[88:89]
	global_load_lds_dwordx4 v[242:243], off
	s_add_u32 m0, s101, 0x2000
	v_lshl_add_u64 v[242:243], v[242:243], 0, v[88:89]
	global_load_lds_dwordx4 v[242:243], off
	s_add_u32 m0, s101, 0x3000
	v_lshl_add_u64 v[242:243], v[242:243], 0, v[88:89]
	global_load_lds_dwordx4 v[242:243], off
	s_add_u32 m0, s101, 0x4000
	v_lshl_add_u64 v[84:85], v[108:109], 0, v[80:81]
	global_load_lds_dwordx4 v[84:85], off
	s_add_u32 m0, s101, 0x5000
	v_lshl_add_u64 v[84:85], v[110:111], 0, v[80:81]
	global_load_lds_dwordx4 v[84:85], off
	s_add_u32 m0, s101, 0x6000
	v_lshl_add_u64 v[84:85], v[112:113], 0, v[80:81]
	global_load_lds_dwordx4 v[84:85], off
	s_add_u32 m0, s101, 0x7000
	v_lshl_add_u64 v[84:85], v[114:115], 0, v[80:81]
	global_load_lds_dwordx4 v[84:85], off
	s_cmp_lg_u32 s99, 0
	s_cbranch_scc1 .La9_var1
	s_lshl_b32 s6, s5, 15
	s_add_i32 s6, s6, 0
	v_lshlrev_b32_e32 v96, 1, v163
	v_lshlrev_b32_e32 v105, 1, v164
	v_add3_u32 v139, s6, v96, v105
	v_add3_u32 v141, s6, v105, v96
	ds_read_b128 v[142:145], v139
	ds_read_b128 v[146:149], v141 offset:2048
	ds_read_b128 v[150:153], v141 offset:4096
	ds_read_b128 v[154:157], v141 offset:6144
	v_lshlrev_b32_e32 v139, 1, v162
	v_add_u32_e32 v141, s6, v139
	v_add_u32_e32 v96, v141, v96
	ds_read_b128 v[172:175], v96 offset:16384
	ds_read_b128 v[176:179], v96 offset:18432
	ds_read_b128 v[180:183], v96 offset:20480
	ds_read_b128 v[184:187], v96 offset:22528
	v_lshlrev_b32_e32 v96, 1, v165
	v_add_u32_e32 v158, s6, v96
	v_add_u32_e32 v105, v158, v105
	ds_read_b128 v[188:191], v105
	ds_read_b128 v[192:195], v105 offset:2048
	ds_read_b128 v[196:199], v105 offset:4096
	ds_read_b128 v[200:203], v105 offset:6144
	v_add_u32_e32 v105, v158, v139
	v_add_u32_e32 v96, v141, v96
	ds_read_b128 v[204:207], v105 offset:16384
	ds_read_b128 v[208:211], v96 offset:18432
	ds_read_b128 v[212:215], v96 offset:20480
	ds_read_b128 v[216:219], v96 offset:22528
	s_waitcnt lgkmcnt(11)
	v_mfma_f32_16x16x32_bf16 v[60:63], v[172:175], v[142:145], v[60:63]
	s_waitcnt lgkmcnt(10)
	v_mfma_f32_16x16x32_bf16 v[56:59], v[176:179], v[142:145], v[56:59]
	s_waitcnt lgkmcnt(9)
	v_mfma_f32_16x16x32_bf16 v[52:55], v[180:183], v[142:145], v[52:55]
	s_waitcnt lgkmcnt(8)
; template <bool ABF, bool BBF, class RowF, class ColF, class Epi>
; __device__ __forceinline__ void gemm_tile(char* smem, int K, RowF rowptr, ColF colptr, int ldb, Epi epi) {
;     ...
;   for (int k0 = 0; k0 < K; k0 += BK) {
;     if (k0 + BK < K) gload(k0 + BK);
;     const u16* As = As0 + cur * (GEMM_SMEM / 2);
;     const u16* Bs = As + BM * LDT;
;     {
;       bf16x8 af[2][4], bfr[2][4];
; #pragma unroll
;       for (int ks = 0; ks < 2; ks++) {
; #pragma unroll
;         for (int mi = 0; mi < 4; mi++) af[ks][mi] = *(const bf16x8*)&As[(wm * 64 + mi * 16 + l15) * LDT + (((ks * 4 + kg) ^ swz) << 3)];
; #pragma unroll
;         for (int ni = 0; ni < 4; ni++) bfr[ks][ni] = *(const bf16x8*)&Bs[(wn * 64 + ni * 16 + l15) * LDT + (((ks * 4 + kg) ^ swz) << 3)];
;       }
;       __builtin_amdgcn_sched_barrier(0);
; #pragma unroll
;       for (int ks = 0; ks < 2; ks++)
; #pragma unroll
;         for (int mi = 0; mi < 4; mi++)
; #pragma unroll
;           for (int ni = 0; ni < 4; ni++)
;             acc[mi][ni] = __builtin_amdgcn_mfma_f32_16x16x32_bf16(bfr[ks][ni], af[ks][mi], acc[mi][ni], 0, 0, 0);
;       __builtin_amdgcn_sched_barrier(0);
;     }
;     if (k0 + BK < K) sstore(cur ^ 1);
;     __syncthreads();
;     cur ^= 1;
;   }
	v_mfma_f32_16x16x32_bf16 v[48:51], v[184:187], v[142:145], v[48:51]
	v_mfma_f32_16x16x32_bf16 v[44:47], v[172:175], v[146:149], v[44:47]
	v_mfma_f32_16x16x32_bf16 v[40:43], v[176:179], v[146:149], v[40:43]
	v_mfma_f32_16x16x32_bf16 v[36:39], v[180:183], v[146:149], v[36:39]
	v_mfma_f32_16x16x32_bf16 v[32:35], v[184:187], v[146:149], v[32:35]
	v_mfma_f32_16x16x32_bf16 v[28:31], v[172:175], v[150:153], v[28:31]
	v_mfma_f32_16x16x32_bf16 v[24:27], v[176:179], v[150:153], v[24:27]
	v_mfma_f32_16x16x32_bf16 v[20:23], v[180:183], v[150:153], v[20:23]
	v_mfma_f32_16x16x32_bf16 v[16:19], v[184:187], v[150:153], v[16:19]
	v_mfma_f32_16x16x32_bf16 v[12:15], v[172:175], v[154:157], v[12:15]
	v_mfma_f32_16x16x32_bf16 v[8:11], v[176:179], v[154:157], v[8:11]
	v_mfma_f32_16x16x32_bf16 v[4:7], v[180:183], v[154:157], v[4:7]
	v_mfma_f32_16x16x32_bf16 v[0:3], v[184:187], v[154:157], v[0:3]
	s_waitcnt lgkmcnt(3)
	v_mfma_f32_16x16x32_bf16 v[60:63], v[204:207], v[188:191], v[60:63]
	s_waitcnt lgkmcnt(2)
	v_mfma_f32_16x16x32_bf16 v[56:59], v[208:211], v[188:191], v[56:59]
	s_waitcnt lgkmcnt(1)
	v_mfma_f32_16x16x32_bf16 v[52:55], v[212:215], v[188:191], v[52:55]
	s_waitcnt lgkmcnt(0)
	v_mfma_f32_16x16x32_bf16 v[48:51], v[216:219], v[188:191], v[48:51]
	v_mfma_f32_16x16x32_bf16 v[44:47], v[204:207], v[192:195], v[44:47]
	v_mfma_f32_16x16x32_bf16 v[40:43], v[208:211], v[192:195], v[40:43]
	v_mfma_f32_16x16x32_bf16 v[36:39], v[212:215], v[192:195], v[36:39]
	v_mfma_f32_16x16x32_bf16 v[32:35], v[216:219], v[192:195], v[32:35]
	v_mfma_f32_16x16x32_bf16 v[28:31], v[204:207], v[196:199], v[28:31]
	v_mfma_f32_16x16x32_bf16 v[24:27], v[208:211], v[196:199], v[24:27]
	v_mfma_f32_16x16x32_bf16 v[20:23], v[212:215], v[196:199], v[20:23]
	v_mfma_f32_16x16x32_bf16 v[16:19], v[216:219], v[196:199], v[16:19]
	v_mfma_f32_16x16x32_bf16 v[12:15], v[204:207], v[200:203], v[12:15]
	v_mfma_f32_16x16x32_bf16 v[8:11], v[208:211], v[200:203], v[8:11]
	v_mfma_f32_16x16x32_bf16 v[4:7], v[212:215], v[200:203], v[4:7]
	v_mfma_f32_16x16x32_bf16 v[0:3], v[216:219], v[200:203], v[0:3]
.La9_ret1:
	s_waitcnt vmcnt(0)
	s_branch .La6_e_X
.La6_c_X:
	s_cmp_lg_u32 s99, 0
	s_cbranch_scc1 .La9_var2
	s_lshl_b32 s6, s5, 15
	s_add_i32 s6, s6, 0
	v_lshlrev_b32_e32 v96, 1, v163
	v_lshlrev_b32_e32 v105, 1, v164
	v_add3_u32 v139, s6, v96, v105
	v_add3_u32 v141, s6, v105, v96
	ds_read_b128 v[142:145], v139
	ds_read_b128 v[146:149], v141 offset:2048
	ds_read_b128 v[150:153], v141 offset:4096
	ds_read_b128 v[154:157], v141 offset:6144
	v_lshlrev_b32_e32 v139, 1, v162
	v_add_u32_e32 v141, s6, v139
	v_add_u32_e32 v96, v141, v96
	ds_read_b128 v[172:175], v96 offset:16384
	ds_read_b128 v[176:179], v96 offset:18432
	ds_read_b128 v[180:183], v96 offset:20480
	ds_read_b128 v[184:187], v96 offset:22528
	v_lshlrev_b32_e32 v96, 1, v165
	v_add_u32_e32 v158, s6, v96
	v_add_u32_e32 v105, v158, v105
	ds_read_b128 v[188:191], v105
	ds_read_b128 v[192:195], v105 offset:2048
	ds_read_b128 v[196:199], v105 offset:4096
	ds_read_b128 v[200:203], v105 offset:6144
	v_add_u32_e32 v105, v158, v139
	v_add_u32_e32 v96, v141, v96
	ds_read_b128 v[204:207], v105 offset:16384
	ds_read_b128 v[208:211], v96 offset:18432
	ds_read_b128 v[212:215], v96 offset:20480
	ds_read_b128 v[216:219], v96 offset:22528
	s_waitcnt lgkmcnt(11)
	v_mfma_f32_16x16x32_bf16 v[60:63], v[172:175], v[142:145], v[60:63]
	s_waitcnt lgkmcnt(10)
	v_mfma_f32_16x16x32_bf16 v[56:59], v[176:179], v[142:145], v[56:59]
	s_waitcnt lgkmcnt(9)
	v_mfma_f32_16x16x32_bf16 v[52:55], v[180:183], v[142:145], v[52:55]
	s_waitcnt lgkmcnt(8)
	v_mfma_f32_16x16x32_bf16 v[48:51], v[184:187], v[142:145], v[48:51]
	v_mfma_f32_16x16x32_bf16 v[44:47], v[172:175], v[146:149], v[44:47]
	v_mfma_f32_16x16x32_bf16 v[40:43], v[176:179], v[146:149], v[40:43]
	v_mfma_f32_16x16x32_bf16 v[36:39], v[180:183], v[146:149], v[36:39]
	v_mfma_f32_16x16x32_bf16 v[32:35], v[184:187], v[146:149], v[32:35]
	v_mfma_f32_16x16x32_bf16 v[28:31], v[172:175], v[150:153], v[28:31]
	v_mfma_f32_16x16x32_bf16 v[24:27], v[176:179], v[150:153], v[24:27]
	v_mfma_f32_16x16x32_bf16 v[20:23], v[180:183], v[150:153], v[20:23]
	v_mfma_f32_16x16x32_bf16 v[16:19], v[184:187], v[150:153], v[16:19]
	v_mfma_f32_16x16x32_bf16 v[12:15], v[172:175], v[154:157], v[12:15]
	v_mfma_f32_16x16x32_bf16 v[8:11], v[176:179], v[154:157], v[8:11]
	v_mfma_f32_16x16x32_bf16 v[4:7], v[180:183], v[154:157], v[4:7]
	v_mfma_f32_16x16x32_bf16 v[0:3], v[184:187], v[154:157], v[0:3]
	s_waitcnt lgkmcnt(3)
	v_mfma_f32_16x16x32_bf16 v[60:63], v[204:207], v[188:191], v[60:63]
	s_waitcnt lgkmcnt(2)
	v_mfma_f32_16x16x32_bf16 v[56:59], v[208:211], v[188:191], v[56:59]
	s_waitcnt lgkmcnt(1)
	v_mfma_f32_16x16x32_bf16 v[52:55], v[212:215], v[188:191], v[52:55]
	s_waitcnt lgkmcnt(0)
	v_mfma_f32_16x16x32_bf16 v[48:51], v[216:219], v[188:191], v[48:51]
	v_mfma_f32_16x16x32_bf16 v[44:47], v[204:207], v[192:195], v[44:47]
	v_mfma_f32_16x16x32_bf16 v[40:43], v[208:211], v[192:195], v[40:43]
	v_mfma_f32_16x16x32_bf16 v[36:39], v[212:215], v[192:195], v[36:39]
	v_mfma_f32_16x16x32_bf16 v[32:35], v[216:219], v[192:195], v[32:35]
	v_mfma_f32_16x16x32_bf16 v[28:31], v[204:207], v[196:199], v[28:31]
	v_mfma_f32_16x16x32_bf16 v[24:27], v[208:211], v[196:199], v[24:27]
	v_mfma_f32_16x16x32_bf16 v[20:23], v[212:215], v[196:199], v[20:23]
	v_mfma_f32_16x16x32_bf16 v[16:19], v[216:219], v[196:199], v[16:19]
	v_mfma_f32_16x16x32_bf16 v[12:15], v[204:207], v[200:203], v[12:15]
	v_mfma_f32_16x16x32_bf16 v[8:11], v[208:211], v[200:203], v[8:11]
	v_mfma_f32_16x16x32_bf16 v[4:7], v[212:215], v[200:203], v[4:7]
	v_mfma_f32_16x16x32_bf16 v[0:3], v[216:219], v[200:203], v[0:3]
.La9_ret2:
.La6_e_X:
	s_add_i32 s4, s4, 64
	s_xor_b32 s5, s5, 1
	v_lshl_add_u64 v[106:107], v[106:107], 0, s[22:23]
	v_lshl_add_u64 v[108:109], v[108:109], 0, s[22:23]
	v_lshl_add_u64 v[110:111], v[110:111], 0, s[22:23]
	v_lshl_add_u64 v[112:113], v[112:113], 0, s[22:23]
	v_lshl_add_u64 v[114:115], v[114:115], 0, s[22:23]
	s_waitcnt lgkmcnt(0)
	s_barrier
	s_cmpk_lt_u32 s4, 0x400
	s_cbranch_scc1 .La6_top_X
